# P9: accumulator offset splats (15 v_mov_b32 per MFMA chain) done as one v_mov_b32 + seven v_mov_b64
# speedup vs baseline: 1.0020x; 1.0015x over previous
.LBB0_1078:
	s_lshl_b32 s0, s10, 7
	v_lshl_add_u64 v[4:5], v[184:185], 0, s[0:1]
	global_load_dwordx4 v[52:55], v[4:5], off offset:96
	global_load_dwordx4 v[56:59], v[4:5], off offset:64
	global_load_dwordx4 v[60:63], v[4:5], off offset:32
	global_load_dwordx4 v[64:67], v[4:5], off
	global_load_dwordx4 v[136:139], v[182:183], off
	global_load_dwordx4 v[140:143], v[182:183], off offset:1024
	global_load_dwordx4 v[144:147], v[182:183], off offset:2048
	global_load_dwordx4 v[132:135], v[182:183], off offset:3072
	global_load_dwordx4 v[80:83], v[188:189], off
	global_load_dwordx4 v[76:79], v[188:189], off offset:1024
	global_load_dwordx4 v[72:75], v[188:189], off offset:2048
	global_load_dwordx4 v[68:71], v[188:189], off offset:3072
	global_load_dwordx4 v[116:119], v[190:191], off
	global_load_dwordx4 v[120:123], v[190:191], off offset:1024
	global_load_dwordx4 v[124:127], v[190:191], off offset:2048
	global_load_dwordx4 v[128:131], v[190:191], off offset:3072
	global_load_dwordx4 v[96:99], v[192:193], off
	global_load_dwordx4 v[92:95], v[192:193], off offset:1024
	global_load_dwordx4 v[88:91], v[192:193], off offset:2048
	global_load_dwordx4 v[84:87], v[192:193], off offset:3072
	global_load_dwordx4 v[104:107], v[194:195], off
	global_load_dwordx4 v[112:115], v[194:195], off offset:1024
	global_load_dwordx4 v[100:103], v[194:195], off offset:2048
	global_load_dwordx4 v[108:111], v[194:195], off offset:3072
	v_mov_b32_e32 v3, v2
	v_mov_b64_e32 v[4:5], v[2:3]
	v_mov_b64_e32 v[6:7], v[2:3]
	v_mov_b64_e32 v[8:9], v[2:3]
	v_mov_b64_e32 v[10:11], v[2:3]
	v_mov_b64_e32 v[12:13], v[2:3]
	v_mov_b64_e32 v[14:15], v[2:3]
	v_mov_b64_e32 v[16:17], v[2:3]
	v_mov_b64_e32 v[34:35], v[16:17]
	v_mov_b64_e32 v[32:33], v[14:15]
	v_mov_b64_e32 v[30:31], v[12:13]
	v_mov_b64_e32 v[28:29], v[10:11]
	v_mov_b64_e32 v[26:27], v[8:9]
	v_mov_b64_e32 v[24:25], v[6:7]
	v_mov_b64_e32 v[22:23], v[4:5]
	v_mov_b64_e32 v[20:21], v[2:3]
	v_mov_b64_e32 v[18:19], v[16:17]
	s_lshl_b32 s0, s10, 6
	s_mov_b32 s11, 0
	s_mov_b32 s14, 5
	v_mov_b32_e32 v208, 0
	s_mov_b64 s[6:7], s[4:5]
	v_mov_b64_e32 v[16:17], v[14:15]
	v_mov_b64_e32 v[14:15], v[12:13]
	v_mov_b64_e32 v[12:13], v[10:11]
	v_mov_b64_e32 v[10:11], v[8:9]
	v_mov_b64_e32 v[8:9], v[6:7]
	v_mov_b64_e32 v[6:7], v[4:5]
	v_mov_b64_e32 v[4:5], v[2:3]
	s_branch .LBB0_1081

.LBB0_1081:
	global_load_dwordx4 v[160:163], v206, s[6:7]
	global_load_dwordx4 v[156:159], v206, s[6:7] offset:1024
	global_load_dwordx4 v[152:155], v206, s[6:7] offset:2048
	global_load_dwordx4 v[148:151], v206, s[6:7] offset:3072
	v_mov_b32 v3, 0
	s_mov_b64 s[6:7], -1
	v_sub_f32_e32 v36, v3, v224
	v_mov_b32_e32 v37, v36
	v_mov_b64_e32 v[38:39], v[36:37]
	v_mov_b64_e32 v[40:41], v[36:37]
	v_mov_b64_e32 v[42:43], v[36:37]
	v_mov_b64_e32 v[44:45], v[36:37]
	v_mov_b64_e32 v[46:47], v[36:37]
	v_mov_b64_e32 v[48:49], v[36:37]
	v_mov_b64_e32 v[50:51], v[36:37]
	s_cmp_gt_i32 s11, s42
	s_waitcnt vmcnt(23)
	v_mfma_f32_32x32x16_bf16 v[36:51], v[136:139], v[64:67], v[36:51]
	s_waitcnt vmcnt(22)
	v_mfma_f32_32x32x16_bf16 v[36:51], v[140:143], v[60:63], v[36:51]
	s_waitcnt vmcnt(21)
	v_mfma_f32_32x32x16_bf16 v[36:51], v[144:147], v[56:59], v[36:51]
	s_waitcnt vmcnt(20)
	v_mfma_f32_32x32x16_bf16 v[36:51], v[132:135], v[52:55], v[36:51]
	s_cbranch_scc1 .LBB0_1083
	s_nop 10
	v_exp_f32_e32 v136, v36
	v_exp_f32_e32 v137, v37
	v_exp_f32_e32 v138, v38
	v_exp_f32_e32 v139, v39
	v_add_f32_e32 v3, v208, v136
	v_exp_f32_e32 v140, v40
	v_add_f32_e32 v3, v137, v3
	v_exp_f32_e32 v141, v41
	v_add_f32_e32 v3, v138, v3
	v_exp_f32_e32 v142, v42
	v_add_f32_e32 v3, v139, v3
	v_exp_f32_e32 v143, v43
	v_add_f32_e32 v3, v140, v3
	v_exp_f32_e32 v144, v44
	v_add_f32_e32 v3, v141, v3
	v_exp_f32_e32 v145, v45
	v_add_f32_e32 v3, v142, v3
	v_exp_f32_e32 v146, v46
	v_add_f32_e32 v3, v143, v3
	v_exp_f32_e32 v147, v47
	v_add_f32_e32 v3, v144, v3
	v_exp_f32_e32 v200, v48
	v_add_f32_e32 v3, v145, v3
	v_exp_f32_e32 v201, v49
	v_add_f32_e32 v3, v146, v3
	v_exp_f32_e32 v202, v50
	v_add_f32_e32 v3, v147, v3
	v_exp_f32_e32 v203, v51
	v_add_f32_e32 v3, v200, v3
	v_add_f32_e32 v3, v201, v3
	v_add_f32_e32 v3, v202, v3
	v_add_f32_e32 v209, v203, v3
	s_mov_b64 s[6:7], 0

.LBB0_1085:
	s_add_i32 s15, s14, -2
	s_min_i32 s16, s15, s9
	s_ashr_i32 s6, s16, 1
	s_ashr_i32 s7, s6, 31
	s_lshl_b64 s[6:7], s[6:7], 13
	s_nop 3
	v_cvt_pk_bf16_f32 v36, v136, v137
	v_cvt_pk_bf16_f32 v37, v138, v139
	v_cvt_pk_bf16_f32 v38, v140, v141
	v_cvt_pk_bf16_f32 v39, v142, v143
	s_add_u32 s17, s52, s6
	s_addc_u32 s18, s53, s7
	s_waitcnt vmcnt(19)
	v_mfma_f32_32x32x16_bf16 v[20:35], v[80:83], v[36:39], v[20:35]
	s_lshl_b32 s16, s16, 12
	s_and_b32 s19, s16, 0x1000
	s_add_u32 s16, s17, s19
	s_addc_u32 s17, s18, 0
	s_add_u32 s6, s2, s6
	s_addc_u32 s7, s3, s7
	s_add_u32 s6, s6, s19
	s_waitcnt vmcnt(18)
	v_mfma_f32_32x32x16_bf16 v[4:19], v[76:79], v[36:39], v[4:19]
	v_cvt_pk_bf16_f32 v40, v144, v145
	v_cvt_pk_bf16_f32 v41, v146, v147
	v_cvt_pk_bf16_f32 v42, v200, v201
	v_cvt_pk_bf16_f32 v43, v202, v203
	s_addc_u32 s7, s7, 0
	global_load_dwordx4 v[136:139], v206, s[16:17]
	global_load_dwordx4 v[140:143], v206, s[16:17] offset:1024
	global_load_dwordx4 v[144:147], v206, s[16:17] offset:2048
	global_load_dwordx4 v[132:135], v206, s[16:17] offset:3072
	s_waitcnt vmcnt(21)
	v_mfma_f32_32x32x16_bf16 v[20:35], v[72:75], v[40:43], v[20:35]
	s_waitcnt vmcnt(20)
	v_mfma_f32_32x32x16_bf16 v[4:19], v[68:71], v[40:43], v[4:19]
	global_load_dwordx4 v[80:83], v206, s[6:7]
	global_load_dwordx4 v[76:79], v206, s[6:7] offset:1024
	global_load_dwordx4 v[72:75], v206, s[6:7] offset:2048
	global_load_dwordx4 v[68:71], v206, s[6:7] offset:3072
	s_add_i32 s6, s14, -4
	s_cmp_ge_u32 s6, s13
	s_cbranch_scc1 .LBB0_1091
	v_mov_b32 v3, 0
	s_add_i32 s6, s11, 32
	v_sub_f32_e32 v36, v3, v224
	v_mov_b32_e32 v37, v36
	v_mov_b64_e32 v[38:39], v[36:37]
	v_mov_b64_e32 v[40:41], v[36:37]
	v_mov_b64_e32 v[42:43], v[36:37]
	v_mov_b64_e32 v[44:45], v[36:37]
	v_mov_b64_e32 v[46:47], v[36:37]
	v_mov_b64_e32 v[48:49], v[36:37]
	v_mov_b64_e32 v[50:51], v[36:37]
	s_cmp_gt_i32 s6, s42
	s_mov_b64 s[6:7], -1
	s_waitcnt vmcnt(23)
	v_mfma_f32_32x32x16_bf16 v[36:51], v[116:119], v[64:67], v[36:51]
	s_waitcnt vmcnt(22)
	v_mfma_f32_32x32x16_bf16 v[36:51], v[120:123], v[60:63], v[36:51]
	s_waitcnt vmcnt(21)
	v_mfma_f32_32x32x16_bf16 v[36:51], v[124:127], v[56:59], v[36:51]
	s_waitcnt vmcnt(20)
	v_mfma_f32_32x32x16_bf16 v[36:51], v[128:131], v[52:55], v[36:51]
	s_nop 11
	v_exp_f32_e32 v116, v36
	v_exp_f32_e32 v117, v37
	v_exp_f32_e32 v118, v38
	v_exp_f32_e32 v119, v39
	v_exp_f32_e32 v120, v40
	v_exp_f32_e32 v121, v41
	v_exp_f32_e32 v122, v42
	v_exp_f32_e32 v43, v43
	v_exp_f32_e32 v36, v44
	v_exp_f32_e32 v3, v45
	v_exp_f32_e32 v38, v46
	v_exp_f32_e32 v37, v47
	v_exp_f32_e32 v40, v48
	v_exp_f32_e32 v39, v49
	v_exp_f32_e32 v42, v50
	v_exp_f32_e32 v41, v51
	s_cbranch_scc1 .LBB0_1088
	v_add_f32_e32 v44, v209, v116
	v_add_f32_e32 v44, v117, v44
	v_add_f32_e32 v44, v118, v44
	v_add_f32_e32 v44, v119, v44
	v_add_f32_e32 v44, v120, v44
	v_add_f32_e32 v44, v121, v44
	v_add_f32_e32 v44, v122, v44
	v_add_f32_e32 v44, v43, v44
	v_add_f32_e32 v44, v36, v44
	v_add_f32_e32 v44, v3, v44
	v_add_f32_e32 v44, v38, v44
	v_add_f32_e32 v44, v37, v44
	v_add_f32_e32 v44, v40, v44
	v_add_f32_e32 v44, v39, v44
	v_add_f32_e32 v44, v42, v44
	v_add_f32_e32 v44, v41, v44
	s_mov_b64 s[6:7], 0

.LBB0_1091:
	s_add_i32 s6, s14, -1
	s_min_i32 s16, s6, s9
	s_ashr_i32 s6, s16, 1
	s_ashr_i32 s7, s6, 31
	s_lshl_b64 s[6:7], s[6:7], 13
	s_add_u32 s17, s52, s6
	s_addc_u32 s18, s53, s7
	s_lshl_b32 s16, s16, 12
	s_and_b32 s19, s16, 0x1000
	s_add_u32 s16, s17, s19
	s_addc_u32 s17, s18, 0
	s_add_u32 s6, s2, s6
	s_addc_u32 s7, s3, s7
	s_add_u32 s6, s6, s19
	s_addc_u32 s7, s7, 0
	global_load_dwordx4 v[116:119], v206, s[16:17]
	global_load_dwordx4 v[120:123], v206, s[16:17] offset:1024
	global_load_dwordx4 v[124:127], v206, s[16:17] offset:2048
	global_load_dwordx4 v[128:131], v206, s[16:17] offset:3072
	global_load_dwordx4 v[96:99], v206, s[6:7]
	global_load_dwordx4 v[92:95], v206, s[6:7] offset:1024
	global_load_dwordx4 v[88:91], v206, s[6:7] offset:2048
	global_load_dwordx4 v[84:87], v206, s[6:7] offset:3072
	s_add_i32 s6, s14, -3
	s_cmp_ge_u32 s6, s13
	s_cbranch_scc1 .LBB0_1096
	v_mov_b32 v3, 0
	s_add_i32 s6, s11, 64
	v_sub_f32_e32 v36, v3, v224
	v_mov_b32_e32 v37, v36
	v_mov_b64_e32 v[38:39], v[36:37]
	v_mov_b64_e32 v[40:41], v[36:37]
	v_mov_b64_e32 v[42:43], v[36:37]
	v_mov_b64_e32 v[44:45], v[36:37]
	v_mov_b64_e32 v[46:47], v[36:37]
	v_mov_b64_e32 v[48:49], v[36:37]
	v_mov_b64_e32 v[50:51], v[36:37]
	s_cmp_gt_i32 s6, s42
	s_mov_b64 s[6:7], -1
	s_waitcnt vmcnt(19)
	v_mfma_f32_32x32x16_bf16 v[36:51], v[160:163], v[64:67], v[36:51]
	s_waitcnt vmcnt(18)
	v_mfma_f32_32x32x16_bf16 v[36:51], v[156:159], v[60:63], v[36:51]
	s_waitcnt vmcnt(17)
	v_mfma_f32_32x32x16_bf16 v[36:51], v[152:155], v[56:59], v[36:51]
	s_waitcnt vmcnt(16)
	v_mfma_f32_32x32x16_bf16 v[36:51], v[148:151], v[52:55], v[36:51]
	s_nop 11
	v_exp_f32_e32 v148, v36
	v_exp_f32_e32 v149, v37
	v_exp_f32_e32 v150, v38
	v_exp_f32_e32 v151, v39
	v_exp_f32_e32 v152, v40
	v_exp_f32_e32 v153, v41
	v_exp_f32_e32 v154, v42
	v_exp_f32_e32 v43, v43
	v_exp_f32_e32 v36, v44
	v_exp_f32_e32 v3, v45
	v_exp_f32_e32 v38, v46
	v_exp_f32_e32 v37, v47
	v_exp_f32_e32 v40, v48
	v_exp_f32_e32 v39, v49
	v_exp_f32_e32 v42, v50
	v_exp_f32_e32 v41, v51
	s_cbranch_scc1 .LBB0_1094
	v_add_f32_e32 v44, v209, v148
	v_add_f32_e32 v44, v149, v44
	v_add_f32_e32 v44, v150, v44
	v_add_f32_e32 v44, v151, v44
	v_add_f32_e32 v44, v152, v44
	v_add_f32_e32 v44, v153, v44
	v_add_f32_e32 v44, v154, v44
	v_add_f32_e32 v44, v43, v44
	v_add_f32_e32 v44, v36, v44
	v_add_f32_e32 v44, v3, v44
	v_add_f32_e32 v44, v38, v44
	v_add_f32_e32 v44, v37, v44
	v_add_f32_e32 v44, v40, v44
	v_add_f32_e32 v44, v39, v44
	v_add_f32_e32 v44, v42, v44
	v_add_f32_e32 v208, v41, v44
	s_mov_b64 s[6:7], 0

.LBB0_1099:
	s_mov_b32 s0, s48
	s_add_i32 s48, s48, 1
	s_cmp_lt_u32 s48, s13
	s_cselect_b32 s4, s48, s0
	s_lshr_b32 s54, s4, 1
	s_lshl_b64 s[0:1], s[54:55], 13
	s_add_u32 s0, s52, s0
	s_addc_u32 s1, s53, s1
	s_lshl_b32 s4, s4, 12
	s_and_b32 s4, s4, 0x1000
	s_add_u32 s0, s0, s4
	s_addc_u32 s1, s1, 0
	global_load_dwordx4 v[66:69], v206, s[0:1]
	global_load_dwordx4 v[70:73], v206, s[0:1] offset:1024
	global_load_dwordx4 v[74:77], v206, s[0:1] offset:2048
	global_load_dwordx4 v[78:81], v206, s[0:1] offset:3072
	v_mov_b32 v2, 0
	s_cmp_le_i32 s43, s42
	v_add_f32_e32 v2, v127, v2
	v_mov_b32_e32 v3, v2
	v_mov_b64_e32 v[4:5], v[2:3]
	v_mov_b64_e32 v[6:7], v[2:3]
	v_mov_b64_e32 v[8:9], v[2:3]
	v_mov_b64_e32 v[10:11], v[2:3]
	v_mov_b64_e32 v[12:13], v[2:3]
	v_mov_b64_e32 v[14:15], v[2:3]
	v_mov_b64_e32 v[16:17], v[2:3]
	s_cselect_b64 s[0:1], -1, 0
	s_cmp_gt_i32 s43, s42
	s_waitcnt vmcnt(4)
	v_mfma_f32_32x32x16_bf16 v[2:17], v[94:97], v[18:21], v[2:17]
	s_mov_b64 s[4:5], -1
	v_mfma_f32_32x32x16_bf16 v[2:17], v[90:93], v[22:25], v[2:17]
	v_mfma_f32_32x32x16_bf16 v[2:17], v[86:89], v[26:29], v[2:17]
	v_mfma_f32_32x32x16_bf16 v[2:17], v[82:85], v[30:33], v[2:17]
	s_nop 11
	v_exp_f32_e32 v125, v2
	v_exp_f32_e32 v124, v3
	v_exp_f32_e32 v123, v4
	v_exp_f32_e32 v122, v5
	v_exp_f32_e32 v121, v6
	v_exp_f32_e32 v120, v7
	v_exp_f32_e32 v119, v8
	v_exp_f32_e32 v118, v9
	v_exp_f32_e32 v9, v10
	v_exp_f32_e32 v8, v11
	v_exp_f32_e32 v7, v12
	v_exp_f32_e32 v6, v13
	v_exp_f32_e32 v5, v14
	v_exp_f32_e32 v4, v15
	v_exp_f32_e32 v3, v16
	v_exp_f32_e32 v2, v17
	s_cbranch_scc1 .LBB0_1101
	v_pk_add_f32 v[102:103], v[124:125], 0 op_sel_hi:[1,0]
	v_pk_add_f32 v[104:105], v[122:123], 0 op_sel_hi:[1,0]
	v_pk_add_f32 v[106:107], v[120:121], 0 op_sel_hi:[1,0]
	v_pk_add_f32 v[108:109], v[118:119], 0 op_sel_hi:[1,0]
	v_pk_add_f32 v[110:111], v[8:9], 0 op_sel_hi:[1,0]
	v_pk_add_f32 v[112:113], v[6:7], 0 op_sel_hi:[1,0]
	v_pk_add_f32 v[114:115], v[4:5], 0 op_sel_hi:[1,0]
	v_pk_add_f32 v[116:117], v[2:3], 0 op_sel_hi:[1,0]
	s_mov_b64 s[4:5], 0

.LBB0_1103:
	v_mov_b32 v2, 0
	v_cndmask_b32_e64 v141, 0, 1, s[0:1]
	v_add_f32_e32 v2, v128, v2
	v_mov_b32_e32 v3, v2
	v_mov_b64_e32 v[4:5], v[2:3]
	v_mov_b64_e32 v[6:7], v[2:3]
	v_mov_b64_e32 v[8:9], v[2:3]
	v_mov_b64_e32 v[10:11], v[2:3]
	v_mov_b64_e32 v[12:13], v[2:3]
	v_mov_b64_e32 v[14:15], v[2:3]
	v_mov_b64_e32 v[16:17], v[2:3]
	v_cmp_ne_u32_e64 s[4:5], 1, v141
	s_andn2_b64 vcc, exec, s[0:1]
	v_mfma_f32_32x32x16_bf16 v[2:17], v[94:97], v[34:37], v[2:17]
	s_mov_b64 s[0:1], -1
	v_mfma_f32_32x32x16_bf16 v[2:17], v[90:93], v[38:41], v[2:17]
	v_mfma_f32_32x32x16_bf16 v[2:17], v[86:89], v[42:45], v[2:17]
	v_mfma_f32_32x32x16_bf16 v[2:17], v[82:85], v[46:49], v[2:17]
	s_nop 11
	v_exp_f32_e32 v140, v2
	v_exp_f32_e32 v139, v3
	v_exp_f32_e32 v138, v4
	v_exp_f32_e32 v137, v5
	v_exp_f32_e32 v136, v6
	v_exp_f32_e32 v135, v7
	v_exp_f32_e32 v134, v8
	v_exp_f32_e32 v133, v9
	v_exp_f32_e32 v125, v10
	v_exp_f32_e32 v124, v11
	v_exp_f32_e32 v123, v12
	v_exp_f32_e32 v122, v13
	v_exp_f32_e32 v121, v14
	v_exp_f32_e32 v120, v15
	v_exp_f32_e32 v119, v16
	v_exp_f32_e32 v118, v17
	s_cbranch_vccnz .LBB0_1105
	s_mov_b64 s[0:1], 0

.LBB0_1107:
	v_mov_b32 v2, 0
	s_and_b64 vcc, exec, s[4:5]
	v_add_f32_e32 v2, v129, v2
	v_mov_b32_e32 v3, v2
	v_mov_b64_e32 v[4:5], v[2:3]
	v_mov_b64_e32 v[6:7], v[2:3]
	v_mov_b64_e32 v[8:9], v[2:3]
	v_mov_b64_e32 v[10:11], v[2:3]
	v_mov_b64_e32 v[12:13], v[2:3]
	v_mov_b64_e32 v[14:15], v[2:3]
	v_mov_b64_e32 v[16:17], v[2:3]
	s_mov_b64 s[0:1], -1
	s_nop 0
	v_mfma_f32_32x32x16_bf16 v[2:17], v[94:97], v[50:53], v[2:17]
	v_mfma_f32_32x32x16_bf16 v[2:17], v[90:93], v[54:57], v[2:17]
	v_mfma_f32_32x32x16_bf16 v[2:17], v[86:89], v[58:61], v[2:17]
	v_mfma_f32_32x32x16_bf16 v[2:17], v[82:85], v[62:65], v[2:17]
	s_nop 11
	v_exp_f32_e32 v189, v2
	v_exp_f32_e32 v188, v3
	v_exp_f32_e32 v187, v4
	v_exp_f32_e32 v186, v5
	v_exp_f32_e32 v185, v6
	v_exp_f32_e32 v184, v7
	v_exp_f32_e32 v183, v8
	v_exp_f32_e32 v182, v9
	v_exp_f32_e32 v166, v10
	v_exp_f32_e32 v163, v11
	v_exp_f32_e32 v162, v12
	v_exp_f32_e32 v161, v13
	v_exp_f32_e32 v160, v14
	v_exp_f32_e32 v159, v15
	v_exp_f32_e32 v158, v16
	v_exp_f32_e32 v157, v17
	s_cbranch_vccnz .LBB0_1109
	s_mov_b64 s[0:1], 0

.LBB0_1111:
	v_mov_b32 v2, 0
	ds_read_b128 v[190:193], v126 offset:16384
	ds_read_b128 v[194:197], v126 offset:17408
	v_add_f32_e32 v2, v130, v2
	v_mov_b32_e32 v3, v2
	v_mov_b64_e32 v[4:5], v[2:3]
	v_mov_b64_e32 v[6:7], v[2:3]
	v_mov_b64_e32 v[8:9], v[2:3]
	v_mov_b64_e32 v[10:11], v[2:3]
	v_mov_b64_e32 v[12:13], v[2:3]
	v_mov_b64_e32 v[14:15], v[2:3]
	v_mov_b64_e32 v[16:17], v[2:3]
	s_and_b64 vcc, exec, s[4:5]
	s_mov_b64 s[0:1], -1
	s_waitcnt lgkmcnt(1)
	v_mfma_f32_32x32x16_bf16 v[2:17], v[94:97], v[190:193], v[2:17]
	s_waitcnt lgkmcnt(0)
	v_mfma_f32_32x32x16_bf16 v[2:17], v[90:93], v[194:197], v[2:17]
	ds_read_b128 v[190:193], v126 offset:18432
	ds_read_b128 v[194:197], v126 offset:19456
	s_waitcnt lgkmcnt(1)
	v_mfma_f32_32x32x16_bf16 v[2:17], v[86:89], v[190:193], v[2:17]
	s_waitcnt lgkmcnt(0)
	v_mfma_f32_32x32x16_bf16 v[2:17], v[82:85], v[194:197], v[2:17]
	s_nop 11
	v_exp_f32_e32 v211, v2
	v_exp_f32_e32 v210, v3
	v_exp_f32_e32 v209, v4
	v_exp_f32_e32 v208, v5
	v_exp_f32_e32 v203, v6
	v_exp_f32_e32 v202, v7
	v_exp_f32_e32 v201, v8
	v_exp_f32_e32 v200, v9
	v_exp_f32_e32 v197, v10
	v_exp_f32_e32 v196, v11
	v_exp_f32_e32 v195, v12
	v_exp_f32_e32 v194, v13
	v_exp_f32_e32 v193, v14
	v_exp_f32_e32 v192, v15
	v_exp_f32_e32 v191, v16
	v_exp_f32_e32 v190, v17
	s_cbranch_vccnz .LBB0_1113
	s_mov_b64 s[0:1], 0

.LBB0_1115:
	v_mov_b32 v2, 0
	ds_read_b128 v[212:215], v126 offset:20480
	ds_read_b128 v[216:219], v126 offset:21504
	v_add_f32_e32 v2, v131, v2
	v_mov_b32_e32 v3, v2
	v_mov_b64_e32 v[4:5], v[2:3]
	v_mov_b64_e32 v[6:7], v[2:3]
	v_mov_b64_e32 v[8:9], v[2:3]
	v_mov_b64_e32 v[10:11], v[2:3]
	v_mov_b64_e32 v[12:13], v[2:3]
	v_mov_b64_e32 v[14:15], v[2:3]
	v_mov_b64_e32 v[16:17], v[2:3]
	s_and_b64 vcc, exec, s[4:5]
	s_mov_b64 s[0:1], -1
	s_waitcnt lgkmcnt(1)
	v_mfma_f32_32x32x16_bf16 v[2:17], v[94:97], v[212:215], v[2:17]
	s_waitcnt lgkmcnt(0)
	v_mfma_f32_32x32x16_bf16 v[2:17], v[90:93], v[216:219], v[2:17]
	ds_read_b128 v[212:215], v126 offset:22528
	ds_read_b128 v[216:219], v126 offset:23552
	s_waitcnt lgkmcnt(1)
	v_mfma_f32_32x32x16_bf16 v[2:17], v[86:89], v[212:215], v[2:17]
	s_waitcnt lgkmcnt(0)
	v_mfma_f32_32x32x16_bf16 v[2:17], v[82:85], v[216:219], v[2:17]
	s_nop 11
	v_exp_f32_e32 v228, v2
	v_exp_f32_e32 v227, v3
	v_exp_f32_e32 v226, v4
	v_exp_f32_e32 v225, v5
	v_exp_f32_e32 v223, v6
	v_exp_f32_e32 v222, v7
	v_exp_f32_e32 v221, v8
	v_exp_f32_e32 v220, v9
	v_exp_f32_e32 v219, v10
	v_exp_f32_e32 v218, v11
	v_exp_f32_e32 v217, v12
	v_exp_f32_e32 v216, v13
	v_exp_f32_e32 v215, v14
	v_exp_f32_e32 v214, v15
	v_exp_f32_e32 v213, v16
	v_exp_f32_e32 v212, v17
	s_cbranch_vccnz .LBB0_1117
	s_mov_b64 s[0:1], 0

.LBB0_1119:
	v_mov_b32 v2, 0
	ds_read_b128 v[230:233], v126 offset:24576
	ds_read_b128 v[234:237], v126 offset:25600
	v_add_f32_e32 v2, v132, v2
	v_mov_b32_e32 v3, v2
	v_mov_b64_e32 v[4:5], v[2:3]
	v_mov_b64_e32 v[6:7], v[2:3]
	v_mov_b64_e32 v[8:9], v[2:3]
	v_mov_b64_e32 v[10:11], v[2:3]
	v_mov_b64_e32 v[12:13], v[2:3]
	v_mov_b64_e32 v[14:15], v[2:3]
	v_mov_b64_e32 v[16:17], v[2:3]
	s_and_b64 vcc, exec, s[4:5]
	s_mov_b64 s[0:1], -1
	s_waitcnt lgkmcnt(1)
	v_mfma_f32_32x32x16_bf16 v[2:17], v[94:97], v[230:233], v[2:17]
	s_waitcnt lgkmcnt(0)
	v_mfma_f32_32x32x16_bf16 v[2:17], v[90:93], v[234:237], v[2:17]
	ds_read_b128 v[90:93], v126 offset:26624
	ds_read_b128 v[94:97], v126 offset:27648
	s_waitcnt lgkmcnt(1)
	v_mfma_f32_32x32x16_bf16 v[2:17], v[86:89], v[90:93], v[2:17]
	s_waitcnt lgkmcnt(0)
	v_mfma_f32_32x32x16_bf16 v[2:17], v[82:85], v[94:97], v[2:17]
	s_nop 11
	v_exp_f32_e32 v89, v2
	v_exp_f32_e32 v88, v3
	v_exp_f32_e32 v87, v4
	v_exp_f32_e32 v86, v5
	v_exp_f32_e32 v85, v6
	v_exp_f32_e32 v84, v7
	v_exp_f32_e32 v83, v8
	v_exp_f32_e32 v82, v9
	v_exp_f32_e32 v9, v10
	v_exp_f32_e32 v8, v11
	v_exp_f32_e32 v7, v12
	v_exp_f32_e32 v6, v13
	v_exp_f32_e32 v5, v14
	v_exp_f32_e32 v4, v15
	v_exp_f32_e32 v3, v16
	v_exp_f32_e32 v2, v17
	s_cbranch_vccnz .LBB0_1121
	s_mov_b64 s[0:1], 0

.LBB0_1140:
	v_mov_b32_e32 v3, v2
	v_mov_b64_e32 v[4:5], v[2:3]
	v_mov_b64_e32 v[6:7], v[2:3]
	v_mov_b64_e32 v[8:9], v[2:3]
	v_mov_b64_e32 v[10:11], v[2:3]
	v_mov_b64_e32 v[12:13], v[2:3]
	v_mov_b64_e32 v[14:15], v[2:3]
	v_mov_b64_e32 v[16:17], v[2:3]
	v_mov_b64_e32 v[32:33], v[16:17]
	s_waitcnt vmcnt(4)
	v_mov_b64_e32 v[48:49], v[16:17]
	v_mov_b32_e32 v197, 0
	v_mov_b64_e32 v[30:31], v[14:15]
	v_mov_b64_e32 v[28:29], v[12:13]
	v_mov_b64_e32 v[26:27], v[10:11]
	v_mov_b64_e32 v[24:25], v[8:9]
	v_mov_b64_e32 v[22:23], v[6:7]
	v_mov_b64_e32 v[20:21], v[4:5]
	v_mov_b64_e32 v[18:19], v[2:3]
	v_mov_b64_e32 v[46:47], v[14:15]
	v_mov_b64_e32 v[44:45], v[12:13]
	v_mov_b64_e32 v[42:43], v[10:11]
	v_mov_b64_e32 v[40:41], v[8:9]
	v_mov_b64_e32 v[38:39], v[6:7]
	v_mov_b64_e32 v[36:37], v[4:5]
	v_mov_b64_e32 v[34:35], v[2:3]

.LBB0_1142:
	s_andn2_b64 vcc, exec, s[6:7]
	s_lshl_b32 s63, s61, 6
	s_cbranch_vccnz .LBB0_1140
	s_lshl_b32 s8, s63, 1
	v_lshl_add_u64 v[4:5], v[210:211], 0, s[8:9]
	global_load_dwordx4 v[66:69], v[4:5], off offset:96
	global_load_dwordx4 v[70:73], v[4:5], off offset:64
	global_load_dwordx4 v[74:77], v[4:5], off offset:32
	global_load_dwordx4 v[78:81], v[4:5], off
	global_load_dwordx4 v[130:133], v[208:209], off
	global_load_dwordx4 v[134:137], v[208:209], off offset:1024
	global_load_dwordx4 v[138:141], v[208:209], off offset:2048
	global_load_dwordx4 v[142:145], v[208:209], off offset:3072
	global_load_dwordx4 v[94:97], v[216:217], off
	global_load_dwordx4 v[90:93], v[216:217], off offset:1024
	global_load_dwordx4 v[86:89], v[216:217], off offset:2048
	global_load_dwordx4 v[82:85], v[216:217], off offset:3072
	global_load_dwordx4 v[146:149], v[218:219], off
	global_load_dwordx4 v[150:153], v[218:219], off offset:1024
	global_load_dwordx4 v[154:157], v[218:219], off offset:2048
	global_load_dwordx4 v[158:161], v[218:219], off offset:3072
	global_load_dwordx4 v[110:113], v[220:221], off
	global_load_dwordx4 v[106:109], v[220:221], off offset:1024
	global_load_dwordx4 v[102:105], v[220:221], off offset:2048
	global_load_dwordx4 v[98:101], v[220:221], off offset:3072
	global_load_dwordx4 v[118:121], v[222:223], off
	global_load_dwordx4 v[126:129], v[222:223], off offset:1024
	global_load_dwordx4 v[114:117], v[222:223], off offset:2048
	global_load_dwordx4 v[122:125], v[222:223], off offset:3072
	v_mov_b32_e32 v3, v2
	v_mov_b64_e32 v[4:5], v[2:3]
	v_mov_b64_e32 v[6:7], v[2:3]
	v_mov_b64_e32 v[8:9], v[2:3]
	v_mov_b64_e32 v[10:11], v[2:3]
	v_mov_b64_e32 v[12:13], v[2:3]
	v_mov_b64_e32 v[14:15], v[2:3]
	v_mov_b64_e32 v[16:17], v[2:3]
	v_mov_b64_e32 v[32:33], v[16:17]
	s_waitcnt vmcnt(28)
	v_mov_b64_e32 v[48:49], v[16:17]
	s_mov_b32 s8, 0
	v_mov_b32_e32 v197, 0
	s_mov_b32 s64, 5
	s_mov_b64 s[12:13], s[28:29]
	v_mov_b64_e32 v[30:31], v[14:15]
	v_mov_b64_e32 v[28:29], v[12:13]
	v_mov_b64_e32 v[26:27], v[10:11]
	v_mov_b64_e32 v[24:25], v[8:9]
	v_mov_b64_e32 v[22:23], v[6:7]
	v_mov_b64_e32 v[20:21], v[4:5]
	v_mov_b64_e32 v[18:19], v[2:3]
	v_mov_b64_e32 v[46:47], v[14:15]
	v_mov_b64_e32 v[44:45], v[12:13]
	v_mov_b64_e32 v[42:43], v[10:11]
	v_mov_b64_e32 v[40:41], v[8:9]
	v_mov_b64_e32 v[38:39], v[6:7]
	v_mov_b64_e32 v[36:37], v[4:5]
	v_mov_b64_e32 v[34:35], v[2:3]
	s_branch .LBB0_1146

.LBB0_1150:
	s_add_i32 s65, s64, -2
	s_min_i32 s66, s65, s62
	s_ashr_i32 s12, s66, 1
	s_ashr_i32 s13, s12, 31
	s_lshl_b64 s[12:13], s[12:13], 13
	v_cvt_pk_bf16_f32 v58, v130, v131
	v_cvt_pk_bf16_f32 v59, v132, v133
	v_cvt_pk_bf16_f32 v60, v134, v55
	v_cvt_pk_bf16_f32 v61, v56, v57
	s_add_u32 s67, s0, s12
	s_addc_u32 s68, s1, s13
	s_waitcnt vmcnt(19)
	v_mfma_f32_32x32x16_bf16 v[18:33], v[94:97], v[58:61], v[18:33]
	s_lshl_b32 s66, s66, 12
	s_and_b32 s69, s66, 0x1000
	s_add_u32 s66, s67, s69
	s_addc_u32 s67, s68, 0
	s_add_u32 s12, s26, s12
	s_addc_u32 s13, s27, s13
	s_add_u32 s12, s12, s69
	s_waitcnt vmcnt(18)
	v_mfma_f32_32x32x16_bf16 v[34:49], v[90:93], v[58:61], v[34:49]
	v_cvt_pk_bf16_f32 v62, v16, v3
	v_cvt_pk_bf16_f32 v63, v50, v17
	v_cvt_pk_bf16_f32 v64, v52, v51
	v_cvt_pk_bf16_f32 v65, v54, v53
	s_addc_u32 s13, s13, 0
	global_load_dwordx4 v[130:133], v204, s[66:67]
	global_load_dwordx4 v[134:137], v204, s[66:67] offset:1024
	global_load_dwordx4 v[138:141], v204, s[66:67] offset:2048
	global_load_dwordx4 v[142:145], v204, s[66:67] offset:3072
	s_waitcnt vmcnt(21)
	v_mfma_f32_32x32x16_bf16 v[18:33], v[86:89], v[62:65], v[18:33]
	s_waitcnt vmcnt(20)
	v_mfma_f32_32x32x16_bf16 v[34:49], v[82:85], v[62:65], v[34:49]
	global_load_dwordx4 v[94:97], v204, s[12:13]
	global_load_dwordx4 v[90:93], v204, s[12:13] offset:1024
	global_load_dwordx4 v[86:89], v204, s[12:13] offset:2048
	global_load_dwordx4 v[82:85], v204, s[12:13] offset:3072
	s_add_i32 s12, s64, -4
	s_cmp_ge_i32 s12, s57
	s_cbranch_scc1 .LBB0_1156
	v_mov_b32 v3, 0
	s_add_i32 s12, s8, 32
	v_sub_f32_e32 v50, v3, v224
	v_mov_b32_e32 v51, v50
	v_mov_b64_e32 v[52:53], v[50:51]
	v_mov_b64_e32 v[54:55], v[50:51]
	v_mov_b64_e32 v[56:57], v[50:51]
	v_mov_b64_e32 v[58:59], v[50:51]
	v_mov_b64_e32 v[60:61], v[50:51]
	v_mov_b64_e32 v[62:63], v[50:51]
	v_mov_b64_e32 v[64:65], v[50:51]
	s_cmp_gt_i32 s12, s58
	s_mov_b64 s[12:13], -1
	s_waitcnt vmcnt(23)
	v_mfma_f32_32x32x16_bf16 v[50:65], v[146:149], v[78:81], v[50:65]
	s_waitcnt vmcnt(22)
	v_mfma_f32_32x32x16_bf16 v[50:65], v[150:153], v[74:77], v[50:65]
	s_waitcnt vmcnt(21)
	v_mfma_f32_32x32x16_bf16 v[50:65], v[154:157], v[70:73], v[50:65]
	s_waitcnt vmcnt(20)
	v_mfma_f32_32x32x16_bf16 v[50:65], v[158:161], v[66:69], v[50:65]
	s_nop 11
	v_exp_f32_e32 v146, v50
	v_exp_f32_e32 v147, v51
	v_exp_f32_e32 v148, v52
	v_exp_f32_e32 v149, v53
	v_exp_f32_e32 v150, v54
	v_exp_f32_e32 v55, v55
	v_exp_f32_e32 v56, v56
	v_exp_f32_e32 v57, v57
	v_exp_f32_e32 v16, v58
	v_exp_f32_e32 v3, v59
	v_exp_f32_e32 v50, v60
	v_exp_f32_e32 v17, v61
	v_exp_f32_e32 v52, v62
	v_exp_f32_e32 v51, v63
	v_exp_f32_e32 v54, v64
	v_exp_f32_e32 v53, v65
	s_cbranch_scc1 .LBB0_1153
	v_add_f32_e32 v58, v201, v146
	v_add_f32_e32 v58, v147, v58
	v_add_f32_e32 v58, v148, v58
	v_add_f32_e32 v58, v149, v58
	v_add_f32_e32 v58, v150, v58
	v_add_f32_e32 v58, v55, v58
	v_add_f32_e32 v58, v56, v58
	v_add_f32_e32 v58, v57, v58
	v_add_f32_e32 v58, v16, v58
	v_add_f32_e32 v58, v3, v58
	v_add_f32_e32 v58, v50, v58
	v_add_f32_e32 v58, v17, v58
	v_add_f32_e32 v58, v52, v58
	v_add_f32_e32 v58, v51, v58
	v_add_f32_e32 v58, v54, v58
	v_add_f32_e32 v58, v53, v58
	s_mov_b64 s[12:13], 0

.LBB0_1156:
	s_add_i32 s12, s64, -1
	s_min_i32 s66, s12, s62
	s_ashr_i32 s12, s66, 1
	s_ashr_i32 s13, s12, 31
	s_lshl_b64 s[12:13], s[12:13], 13
	s_add_u32 s67, s0, s12
	s_addc_u32 s68, s1, s13
	s_lshl_b32 s66, s66, 12
	s_and_b32 s69, s66, 0x1000
	s_add_u32 s66, s67, s69
	s_addc_u32 s67, s68, 0
	s_add_u32 s12, s26, s12
	s_addc_u32 s13, s27, s13
	s_add_u32 s12, s12, s69
	s_addc_u32 s13, s13, 0
	global_load_dwordx4 v[146:149], v204, s[66:67]
	global_load_dwordx4 v[150:153], v204, s[66:67] offset:1024
	global_load_dwordx4 v[154:157], v204, s[66:67] offset:2048
	global_load_dwordx4 v[158:161], v204, s[66:67] offset:3072
	global_load_dwordx4 v[110:113], v204, s[12:13]
	global_load_dwordx4 v[106:109], v204, s[12:13] offset:1024
	global_load_dwordx4 v[102:105], v204, s[12:13] offset:2048
	global_load_dwordx4 v[98:101], v204, s[12:13] offset:3072
	s_add_i32 s12, s64, -3
	s_cmp_ge_i32 s12, s57
	s_cbranch_scc1 .LBB0_1161
	v_mov_b32 v3, 0
	s_add_i32 s12, s8, 64
	v_sub_f32_e32 v50, v3, v224
	v_mov_b32_e32 v51, v50
	v_mov_b64_e32 v[52:53], v[50:51]
	v_mov_b64_e32 v[54:55], v[50:51]
	v_mov_b64_e32 v[56:57], v[50:51]
	v_mov_b64_e32 v[58:59], v[50:51]
	v_mov_b64_e32 v[60:61], v[50:51]
	v_mov_b64_e32 v[62:63], v[50:51]
	v_mov_b64_e32 v[64:65], v[50:51]
	s_cmp_gt_i32 s12, s58
	s_mov_b64 s[12:13], -1
	s_waitcnt vmcnt(19)
	v_mfma_f32_32x32x16_bf16 v[50:65], v[162:165], v[78:81], v[50:65]
	s_waitcnt vmcnt(18)
	v_mfma_f32_32x32x16_bf16 v[50:65], v[12:15], v[74:77], v[50:65]
	s_waitcnt vmcnt(17)
	v_mfma_f32_32x32x16_bf16 v[50:65], v[8:11], v[70:73], v[50:65]
	s_waitcnt vmcnt(16)
	v_mfma_f32_32x32x16_bf16 v[50:65], v[4:7], v[66:69], v[50:65]
	s_nop 11
	v_exp_f32_e32 v12, v50
	v_exp_f32_e32 v11, v51
	v_exp_f32_e32 v14, v52
	v_exp_f32_e32 v13, v53
	v_exp_f32_e32 v16, v54
	v_exp_f32_e32 v15, v55
	v_exp_f32_e32 v50, v56
	v_exp_f32_e32 v17, v57
	v_exp_f32_e32 v4, v58
	v_exp_f32_e32 v3, v59
	v_exp_f32_e32 v6, v60
	v_exp_f32_e32 v5, v61
	v_exp_f32_e32 v8, v62
	v_exp_f32_e32 v7, v63
	v_exp_f32_e32 v10, v64
	v_exp_f32_e32 v9, v65
	s_cbranch_scc1 .LBB0_1159
	v_add_f32_e32 v51, v201, v12
	v_add_f32_e32 v51, v11, v51
	v_add_f32_e32 v51, v14, v51
	v_add_f32_e32 v51, v13, v51
	v_add_f32_e32 v51, v16, v51
	v_add_f32_e32 v51, v15, v51
	v_add_f32_e32 v51, v50, v51
	v_add_f32_e32 v51, v17, v51
	v_add_f32_e32 v51, v4, v51
	v_add_f32_e32 v51, v3, v51
	v_add_f32_e32 v51, v6, v51
	v_add_f32_e32 v51, v5, v51
	v_add_f32_e32 v51, v8, v51
	v_add_f32_e32 v51, v7, v51
	v_add_f32_e32 v51, v10, v51
	v_add_f32_e32 v197, v9, v51
	s_mov_b64 s[12:13], 0

.LBB0_1165:
	s_mov_b32 s6, s28
	s_add_i32 s28, s28, 1
	s_cmp_lt_i32 s28, s57
	s_cselect_b32 s12, s28, s6
	s_lshr_b32 s8, s12, 1
	s_lshl_b64 s[6:7], s[8:9], 13
	s_add_u32 s6, s0, s6
	s_addc_u32 s7, s1, s7
	s_lshl_b32 s8, s12, 12
	s_and_b32 s8, s8, 0x1000
	s_add_u32 s6, s6, s8
	s_addc_u32 s7, s7, 0
	global_load_dwordx4 v[68:71], v204, s[6:7]
	global_load_dwordx4 v[72:75], v204, s[6:7] offset:1024
	global_load_dwordx4 v[76:79], v204, s[6:7] offset:2048
	global_load_dwordx4 v[80:83], v204, s[6:7] offset:3072
	v_mov_b32 v4, 0
	s_cmp_le_i32 s26, s58
	v_add_f32_e32 v4, v126, v4
	v_mov_b32_e32 v5, v4
	v_mov_b64_e32 v[6:7], v[4:5]
	v_mov_b64_e32 v[8:9], v[4:5]
	v_mov_b64_e32 v[10:11], v[4:5]
	v_mov_b64_e32 v[12:13], v[4:5]
	v_mov_b64_e32 v[14:15], v[4:5]
	v_mov_b64_e32 v[16:17], v[4:5]
	v_mov_b64_e32 v[18:19], v[4:5]
	s_cselect_b64 s[12:13], -1, 0
	s_cmp_gt_i32 s26, s58
	s_waitcnt vmcnt(4)
	v_mfma_f32_32x32x16_bf16 v[4:19], v[96:99], v[20:23], v[4:19]
	s_mov_b64 s[6:7], -1
	v_mfma_f32_32x32x16_bf16 v[4:19], v[92:95], v[24:27], v[4:19]
	v_mfma_f32_32x32x16_bf16 v[4:19], v[88:91], v[28:31], v[4:19]
	v_mfma_f32_32x32x16_bf16 v[4:19], v[84:87], v[32:35], v[4:19]
	s_nop 11
	v_exp_f32_e32 v125, v4
	v_exp_f32_e32 v124, v5
	v_exp_f32_e32 v123, v6
	v_exp_f32_e32 v122, v7
	v_exp_f32_e32 v121, v8
	v_exp_f32_e32 v120, v9
	v_exp_f32_e32 v119, v10
	v_exp_f32_e32 v118, v11
	v_exp_f32_e32 v11, v12
	v_exp_f32_e32 v10, v13
	v_exp_f32_e32 v9, v14
	v_exp_f32_e32 v8, v15
	v_exp_f32_e32 v7, v16
	v_exp_f32_e32 v6, v17
	v_exp_f32_e32 v5, v18
	v_exp_f32_e32 v4, v19
	s_cbranch_scc1 .LBB0_1167
	v_pk_add_f32 v[102:103], v[124:125], 0 op_sel_hi:[1,0]
	v_pk_add_f32 v[104:105], v[122:123], 0 op_sel_hi:[1,0]
	v_pk_add_f32 v[106:107], v[120:121], 0 op_sel_hi:[1,0]
	v_pk_add_f32 v[108:109], v[118:119], 0 op_sel_hi:[1,0]
	v_pk_add_f32 v[110:111], v[10:11], 0 op_sel_hi:[1,0]
	v_pk_add_f32 v[112:113], v[8:9], 0 op_sel_hi:[1,0]
	v_pk_add_f32 v[114:115], v[6:7], 0 op_sel_hi:[1,0]
	v_pk_add_f32 v[116:117], v[4:5], 0 op_sel_hi:[1,0]
	s_mov_b64 s[6:7], 0

.LBB0_1169:
	v_mov_b32 v4, 0
	v_cndmask_b32_e64 v141, 0, 1, s[12:13]
	v_add_f32_e32 v4, v127, v4
	v_mov_b32_e32 v5, v4
	v_mov_b64_e32 v[6:7], v[4:5]
	v_mov_b64_e32 v[8:9], v[4:5]
	v_mov_b64_e32 v[10:11], v[4:5]
	v_mov_b64_e32 v[12:13], v[4:5]
	v_mov_b64_e32 v[14:15], v[4:5]
	v_mov_b64_e32 v[16:17], v[4:5]
	v_mov_b64_e32 v[18:19], v[4:5]
	v_cmp_ne_u32_e64 s[6:7], 1, v141
	s_andn2_b64 vcc, exec, s[12:13]
	v_mfma_f32_32x32x16_bf16 v[4:19], v[96:99], v[36:39], v[4:19]
	s_mov_b64 s[12:13], -1
	v_mfma_f32_32x32x16_bf16 v[4:19], v[92:95], v[40:43], v[4:19]
	v_mfma_f32_32x32x16_bf16 v[4:19], v[88:91], v[44:47], v[4:19]
	v_mfma_f32_32x32x16_bf16 v[4:19], v[84:87], v[48:51], v[4:19]
	s_nop 11
	v_exp_f32_e32 v140, v4
	v_exp_f32_e32 v139, v5
	v_exp_f32_e32 v138, v6
	v_exp_f32_e32 v137, v7
	v_exp_f32_e32 v136, v8
	v_exp_f32_e32 v135, v9
	v_exp_f32_e32 v134, v10
	v_exp_f32_e32 v133, v11
	v_exp_f32_e32 v125, v12
	v_exp_f32_e32 v124, v13
	v_exp_f32_e32 v123, v14
	v_exp_f32_e32 v122, v15
	v_exp_f32_e32 v121, v16
	v_exp_f32_e32 v120, v17
	v_exp_f32_e32 v119, v18
	v_exp_f32_e32 v118, v19
	s_cbranch_vccnz .LBB0_1171
	s_mov_b64 s[12:13], 0

.LBB0_1173:
	v_mov_b32 v4, 0
	s_and_b64 vcc, exec, s[6:7]
	v_add_f32_e32 v4, v128, v4
	v_mov_b32_e32 v5, v4
	v_mov_b64_e32 v[6:7], v[4:5]
	v_mov_b64_e32 v[8:9], v[4:5]
	v_mov_b64_e32 v[10:11], v[4:5]
	v_mov_b64_e32 v[12:13], v[4:5]
	v_mov_b64_e32 v[14:15], v[4:5]
	v_mov_b64_e32 v[16:17], v[4:5]
	v_mov_b64_e32 v[18:19], v[4:5]
	s_mov_b64 s[12:13], -1
	s_nop 0
	v_mfma_f32_32x32x16_bf16 v[4:19], v[96:99], v[52:55], v[4:19]
	v_mfma_f32_32x32x16_bf16 v[4:19], v[92:95], v[56:59], v[4:19]
	v_mfma_f32_32x32x16_bf16 v[4:19], v[88:91], v[60:63], v[4:19]
	v_mfma_f32_32x32x16_bf16 v[4:19], v[84:87], v[64:67], v[4:19]
	s_nop 11
	v_exp_f32_e32 v209, v4
	v_exp_f32_e32 v208, v5
	v_exp_f32_e32 v205, v6
	v_exp_f32_e32 v203, v7
	v_exp_f32_e32 v201, v8
	v_exp_f32_e32 v197, v9
	v_exp_f32_e32 v165, v10
	v_exp_f32_e32 v164, v11
	v_exp_f32_e32 v163, v12
	v_exp_f32_e32 v162, v13
	v_exp_f32_e32 v161, v14
	v_exp_f32_e32 v160, v15
	v_exp_f32_e32 v159, v16
	v_exp_f32_e32 v158, v17
	v_exp_f32_e32 v157, v18
	v_exp_f32_e32 v156, v19
	s_cbranch_vccnz .LBB0_1175
	s_mov_b64 s[12:13], 0

.LBB0_1177:
	v_mov_b32 v4, 0
	ds_read_b128 v[210:213], v193 offset:16384
	ds_read_b128 v[214:217], v193 offset:17408
	v_add_f32_e32 v4, v129, v4
	v_mov_b32_e32 v5, v4
	v_mov_b64_e32 v[6:7], v[4:5]
	v_mov_b64_e32 v[8:9], v[4:5]
	v_mov_b64_e32 v[10:11], v[4:5]
	v_mov_b64_e32 v[12:13], v[4:5]
	v_mov_b64_e32 v[14:15], v[4:5]
	v_mov_b64_e32 v[16:17], v[4:5]
	v_mov_b64_e32 v[18:19], v[4:5]
	s_and_b64 vcc, exec, s[6:7]
	s_mov_b64 s[12:13], -1
	s_waitcnt lgkmcnt(1)
	v_mfma_f32_32x32x16_bf16 v[4:19], v[96:99], v[210:213], v[4:19]
	s_waitcnt lgkmcnt(0)
	v_mfma_f32_32x32x16_bf16 v[4:19], v[92:95], v[214:217], v[4:19]
	ds_read_b128 v[210:213], v193 offset:18432
	ds_read_b128 v[214:217], v193 offset:19456
	s_waitcnt lgkmcnt(1)
	v_mfma_f32_32x32x16_bf16 v[4:19], v[88:91], v[210:213], v[4:19]
	s_waitcnt lgkmcnt(0)
	v_mfma_f32_32x32x16_bf16 v[4:19], v[84:87], v[214:217], v[4:19]
	s_nop 11
	v_exp_f32_e32 v226, v4
	v_exp_f32_e32 v225, v5
	v_exp_f32_e32 v223, v6
	v_exp_f32_e32 v222, v7
	v_exp_f32_e32 v221, v8
	v_exp_f32_e32 v220, v9
	v_exp_f32_e32 v219, v10
	v_exp_f32_e32 v218, v11
	v_exp_f32_e32 v217, v12
	v_exp_f32_e32 v216, v13
	v_exp_f32_e32 v215, v14
	v_exp_f32_e32 v214, v15
	v_exp_f32_e32 v213, v16
	v_exp_f32_e32 v212, v17
	v_exp_f32_e32 v211, v18
	v_exp_f32_e32 v210, v19
	s_cbranch_vccnz .LBB0_1179
	s_mov_b64 s[12:13], 0

.LBB0_1181:
	v_mov_b32 v4, 0
	ds_read_b128 v[228:231], v193 offset:20480
	ds_read_b128 v[232:235], v193 offset:21504
	v_add_f32_e32 v4, v130, v4
	v_mov_b32_e32 v5, v4
	v_mov_b64_e32 v[6:7], v[4:5]
	v_mov_b64_e32 v[8:9], v[4:5]
	v_mov_b64_e32 v[10:11], v[4:5]
	v_mov_b64_e32 v[12:13], v[4:5]
	v_mov_b64_e32 v[14:15], v[4:5]
	v_mov_b64_e32 v[16:17], v[4:5]
	v_mov_b64_e32 v[18:19], v[4:5]
	s_and_b64 vcc, exec, s[6:7]
	s_mov_b64 s[12:13], -1
	s_waitcnt lgkmcnt(1)
	v_mfma_f32_32x32x16_bf16 v[4:19], v[96:99], v[228:231], v[4:19]
	s_waitcnt lgkmcnt(0)
	v_mfma_f32_32x32x16_bf16 v[4:19], v[92:95], v[232:235], v[4:19]
	ds_read_b128 v[228:231], v193 offset:22528
	ds_read_b128 v[232:235], v193 offset:23552
	s_waitcnt lgkmcnt(1)
	v_mfma_f32_32x32x16_bf16 v[4:19], v[88:91], v[228:231], v[4:19]
	s_waitcnt lgkmcnt(0)
	v_mfma_f32_32x32x16_bf16 v[4:19], v[84:87], v[232:235], v[4:19]
	s_nop 11
	v_exp_f32_e32 v242, v4
	v_exp_f32_e32 v241, v5
	v_exp_f32_e32 v240, v6
	v_exp_f32_e32 v239, v7
	v_exp_f32_e32 v238, v8
	v_exp_f32_e32 v237, v9
	v_exp_f32_e32 v236, v10
	v_exp_f32_e32 v235, v11
	v_exp_f32_e32 v234, v12
	v_exp_f32_e32 v233, v13
	v_exp_f32_e32 v232, v14
	v_exp_f32_e32 v231, v15
	v_exp_f32_e32 v230, v16
	v_exp_f32_e32 v229, v17
	v_exp_f32_e32 v228, v18
	v_exp_f32_e32 v227, v19
	s_cbranch_vccnz .LBB0_1183
	s_mov_b64 s[12:13], 0

.LBB0_1185:
	v_mov_b32 v4, 0
	ds_read_b128 v[244:247], v193 offset:24576
	ds_read_b128 v[248:251], v193 offset:25600
	v_add_f32_e32 v4, v131, v4
	v_mov_b32_e32 v5, v4
	v_mov_b64_e32 v[6:7], v[4:5]
	v_mov_b64_e32 v[8:9], v[4:5]
	v_mov_b64_e32 v[10:11], v[4:5]
	v_mov_b64_e32 v[12:13], v[4:5]
	v_mov_b64_e32 v[14:15], v[4:5]
	v_mov_b64_e32 v[16:17], v[4:5]
	v_mov_b64_e32 v[18:19], v[4:5]
	s_and_b64 vcc, exec, s[6:7]
	s_mov_b64 s[6:7], -1
	s_waitcnt lgkmcnt(1)
	v_mfma_f32_32x32x16_bf16 v[4:19], v[96:99], v[244:247], v[4:19]
	s_waitcnt lgkmcnt(0)
	v_mfma_f32_32x32x16_bf16 v[4:19], v[92:95], v[248:251], v[4:19]
	ds_read_b128 v[92:95], v193 offset:26624
	ds_read_b128 v[96:99], v193 offset:27648
	s_waitcnt lgkmcnt(1)
	v_mfma_f32_32x32x16_bf16 v[4:19], v[88:91], v[92:95], v[4:19]
	s_waitcnt lgkmcnt(0)
	v_mfma_f32_32x32x16_bf16 v[4:19], v[84:87], v[96:99], v[4:19]
	s_nop 11
	v_exp_f32_e32 v91, v4
	v_exp_f32_e32 v90, v5
	v_exp_f32_e32 v89, v6
	v_exp_f32_e32 v88, v7
	v_exp_f32_e32 v87, v8
	v_exp_f32_e32 v86, v9
	v_exp_f32_e32 v85, v10
	v_exp_f32_e32 v84, v11
	v_exp_f32_e32 v11, v12
	v_exp_f32_e32 v10, v13
	v_exp_f32_e32 v9, v14
	v_exp_f32_e32 v8, v15
	v_exp_f32_e32 v7, v16
	v_exp_f32_e32 v6, v17
	v_exp_f32_e32 v5, v18
	v_exp_f32_e32 v4, v19
	s_cbranch_vccnz .LBB0_1187
	s_mov_b64 s[6:7], 0

.LBB0_1190:
	s_and_b64 vcc, exec, s[0:1]
	s_cbranch_vccz .LBB0_1131
	s_and_b32 s0, s56, 0xffff
	s_mul_i32 s0, s0, 0xaaab
	s_lshr_b32 s0, s0, 19
	s_mul_i32 s1, s0, 12
	s_sub_i32 s1, s56, s1
	s_lshl_b32 s0, s0, 5
	s_and_b32 s13, s1, 0xffff
	s_add_i32 s1, s0, 0xfffffe00
	s_cmpk_gt_u32 s56, 0xbf
	s_cselect_b32 s26, s1, 0
	v_or_b32_e32 v3, s0, v185
	s_sub_i32 s0, s0, s26
	s_add_i32 s0, s0, 32
	s_lshl_b32 s12, s13, 6
	s_ashr_i32 s27, s0, 5
	v_mov_b32_e32 v132, 0
	s_cmp_lt_i32 s27, 1
	v_mov_b32_e32 v134, 0
	s_waitcnt lgkmcnt(12)
	v_mov_b32_e32 v4, 0
	v_mov_b32_e32 v5, 0
	v_mov_b32_e32 v6, 0
	v_mov_b32_e32 v7, 0
	v_mov_b32_e32 v8, 0
	v_mov_b32_e32 v9, 0
	v_mov_b32_e32 v10, 0
	v_mov_b32_e32 v11, 0
	v_mov_b32_e32 v12, 0
	v_mov_b32_e32 v13, 0
	v_mov_b32_e32 v14, 0
	v_mov_b32_e32 v15, 0
	v_mov_b32_e32 v16, 0
	v_mov_b32_e32 v17, 0
	v_mov_b32_e32 v18, 0
	v_mov_b32_e32 v19, 0
	v_mov_b32_e32 v20, 0
	v_mov_b32_e32 v21, 0
	v_mov_b32_e32 v22, 0
	v_mov_b32_e32 v23, 0
	v_mov_b32_e32 v24, 0
	v_mov_b32_e32 v25, 0
	v_mov_b32_e32 v26, 0
	v_mov_b32_e32 v27, 0
	v_mov_b32_e32 v28, 0
	v_mov_b32_e32 v29, 0
	v_mov_b32_e32 v30, 0
	v_mov_b32_e32 v31, 0
	v_mov_b32_e32 v32, 0
	v_mov_b32_e32 v33, 0
	v_mov_b32_e32 v34, 0
	v_mov_b32_e32 v35, 0
	s_cbranch_scc1 .LBB0_1200
	s_cmp_gt_u32 s13, 5
	s_cselect_b32 s1, 0x200000, 0
	s_add_u32 s28, s34, s1
	s_addc_u32 s29, s35, 0
	s_add_u32 s56, s36, s1
	s_addc_u32 s57, s37, 0
	s_ashr_i32 s6, s26, 6
	s_ashr_i32 s7, s6, 31
	v_mul_u32_u24_e32 v4, 0x300, v3
	v_mov_b32_e32 v5, v2
	s_lshl_b32 s8, s12, 1
	s_lshl_b64 s[6:7], s[6:7], 13
	v_lshl_add_u64 v[4:5], v[4:5], 1, s[10:11]
	s_add_u32 s1, s28, s6
	v_lshl_add_u64 v[4:5], v[4:5], 0, s[8:9]
	s_addc_u32 s8, s29, s7
	s_lshl_b32 s58, s26, 7
	s_and_b32 s60, s58, 0x1000
	s_add_u32 s58, s1, s60
	s_addc_u32 s59, s8, 0
	s_add_u32 s1, s56, s6
	s_addc_u32 s7, s57, s7
	v_lshlrev_b32_e32 v6, 1, v166
	v_mov_b32_e32 v7, v2
	s_add_u32 s6, s1, s60
	v_lshl_add_u64 v[4:5], v[4:5], 0, v[6:7]
	s_addc_u32 s7, s7, 0
	global_load_dwordx4 v[68:71], v[4:5], off offset:96
	global_load_dwordx4 v[72:75], v[4:5], off offset:64
	global_load_dwordx4 v[76:79], v[4:5], off offset:32
	global_load_dwordx4 v[80:83], v[4:5], off
	global_load_dwordx4 v[36:39], v204, s[58:59] offset:3072
	global_load_dwordx4 v[40:43], v204, s[58:59] offset:2048
	global_load_dwordx4 v[44:47], v204, s[58:59] offset:1024
	global_load_dwordx4 v[20:23], v204, s[58:59]
	global_load_dwordx4 v[24:27], v204, s[6:7] offset:3072
	global_load_dwordx4 v[28:31], v204, s[6:7] offset:2048
	global_load_dwordx4 v[32:35], v204, s[6:7] offset:1024
	global_load_dwordx4 v[48:51], v204, s[6:7]
	s_cmp_eq_u32 s0, 32
	s_cselect_b64 s[0:1], -1, 0
	s_and_b64 vcc, s[0:1], exec
	s_cselect_b32 s0, 0, 32
	s_add_i32 s6, s0, s26
	s_ashr_i32 s0, s6, 6
	s_ashr_i32 s1, s0, 31
	s_lshl_b64 s[0:1], s[0:1], 13
	s_add_u32 s7, s56, s0
	s_addc_u32 s8, s57, s1
	s_lshl_b32 s6, s6, 7
	s_and_b32 s58, s6, 0x1000
	s_add_u32 s6, s7, s58
	s_addc_u32 s7, s8, 0
	s_add_u32 s0, s28, s0
	s_addc_u32 s1, s29, s1
	s_add_u32 s0, s0, s58
	s_addc_u32 s1, s1, 0
	global_load_dwordx4 v[88:91], v204, s[6:7]
	global_load_dwordx4 v[100:103], v204, s[6:7] offset:1024
	global_load_dwordx4 v[96:99], v204, s[6:7] offset:2048
	global_load_dwordx4 v[104:107], v204, s[6:7] offset:3072
	global_load_dwordx4 v[112:115], v204, s[0:1]
	global_load_dwordx4 v[108:111], v204, s[0:1] offset:1024
	global_load_dwordx4 v[92:95], v204, s[0:1] offset:2048
	global_load_dwordx4 v[84:87], v204, s[0:1] offset:3072
	v_mov_b32 v4, 0
	v_add_u32_e32 v133, 0xfffffe00, v3
	v_sub_f32_e32 v4, v4, v183
	v_mov_b32_e32 v5, v4
	v_mov_b64_e32 v[6:7], v[4:5]
	v_mov_b64_e32 v[8:9], v[4:5]
	v_mov_b64_e32 v[10:11], v[4:5]
	v_mov_b64_e32 v[12:13], v[4:5]
	v_mov_b64_e32 v[14:15], v[4:5]
	v_mov_b64_e32 v[16:17], v[4:5]
	v_mov_b64_e32 v[18:19], v[4:5]
	s_waitcnt vmcnt(8)
	s_nop 0
	v_mfma_f32_32x32x16_bf16 v[4:19], v[48:51], v[80:83], v[4:19]
	v_mfma_f32_32x32x16_bf16 v[4:19], v[32:35], v[76:79], v[4:19]
	v_mfma_f32_32x32x16_bf16 v[4:19], v[28:31], v[72:75], v[4:19]
	v_mfma_f32_32x32x16_bf16 v[4:19], v[24:27], v[68:71], v[4:19]
	v_or_b32_e32 v24, s26, v168
	v_cmp_le_i32_e64 s[0:1], v24, v3
	v_cmp_gt_i32_e64 s[6:7], v24, v133
	s_and_b64 s[0:1], s[0:1], s[6:7]
	v_cmp_ge_i32_e64 s[6:7], v24, v133
	v_or_b32_e32 v25, 2, v24
	s_nop 5
	v_exp_f32_e32 v4, v4
	v_exp_f32_e32 v5, v5
	v_exp_f32_e32 v6, v6
	v_exp_f32_e32 v7, v7
	v_cndmask_b32_e64 v4, 0, v4, s[0:1]
	v_cmp_lt_i32_e64 s[0:1], v24, v3
	s_and_b64 s[0:1], s[0:1], s[6:7]
	v_cmp_gt_i32_e64 s[6:7], v25, v133
	v_cndmask_b32_e64 v5, 0, v5, s[0:1]
	v_cmp_le_i32_e64 s[0:1], v25, v3
	s_and_b64 s[0:1], s[0:1], s[6:7]
	v_or_b32_e32 v25, 3, v24
	v_cndmask_b32_e64 v6, 0, v6, s[0:1]
	v_cmp_le_i32_e64 s[0:1], v25, v3
	v_cmp_gt_i32_e64 s[6:7], v25, v133
	v_exp_f32_e32 v8, v8
	s_and_b64 s[0:1], s[0:1], s[6:7]
	v_or_b32_e32 v25, 8, v24
	v_cndmask_b32_e64 v7, 0, v7, s[0:1]
	v_cmp_le_i32_e64 s[0:1], v25, v3
	v_cmp_gt_i32_e64 s[6:7], v25, v133
	v_exp_f32_e32 v9, v9
	s_and_b64 s[0:1], s[0:1], s[6:7]
	v_or_b32_e32 v25, 9, v24
	v_cndmask_b32_e64 v8, 0, v8, s[0:1]
	v_cmp_le_i32_e64 s[0:1], v25, v3
	v_cmp_gt_i32_e64 s[6:7], v25, v133
	v_exp_f32_e32 v10, v10
	s_and_b64 s[0:1], s[0:1], s[6:7]
	v_or_b32_e32 v25, 10, v24
	v_cndmask_b32_e64 v9, 0, v9, s[0:1]
	v_cmp_le_i32_e64 s[0:1], v25, v3
	v_cmp_gt_i32_e64 s[6:7], v25, v133
	v_exp_f32_e32 v11, v11
	s_and_b64 s[0:1], s[0:1], s[6:7]
	v_or_b32_e32 v25, 11, v24
	v_cndmask_b32_e64 v10, 0, v10, s[0:1]
	v_cmp_le_i32_e64 s[0:1], v25, v3
	v_cmp_gt_i32_e64 s[6:7], v25, v133
	v_exp_f32_e32 v12, v12
	s_and_b64 s[0:1], s[0:1], s[6:7]
	v_or_b32_e32 v25, 16, v24
	v_cndmask_b32_e64 v11, 0, v11, s[0:1]
	v_cmp_le_i32_e64 s[0:1], v25, v3
	v_cmp_gt_i32_e64 s[6:7], v25, v133
	s_and_b64 s[0:1], s[0:1], s[6:7]
	v_cndmask_b32_e64 v48, 0, v12, s[0:1]
	v_or_b32_e32 v12, 17, v24
	v_cmp_le_i32_e64 s[0:1], v12, v3
	v_cmp_gt_i32_e64 s[6:7], v12, v133
	v_exp_f32_e32 v12, v13
	s_and_b64 s[0:1], s[0:1], s[6:7]
	v_cndmask_b32_e64 v49, 0, v12, s[0:1]
	v_or_b32_e32 v12, 18, v24
	v_cmp_le_i32_e64 s[0:1], v12, v3
	v_cmp_gt_i32_e64 s[6:7], v12, v133
	v_exp_f32_e32 v12, v14
	s_and_b64 s[0:1], s[0:1], s[6:7]
	v_cndmask_b32_e64 v50, 0, v12, s[0:1]
	v_or_b32_e32 v12, 19, v24
	v_cmp_le_i32_e64 s[0:1], v12, v3
	v_cmp_gt_i32_e64 s[6:7], v12, v133
	v_exp_f32_e32 v12, v15
	s_and_b64 s[0:1], s[0:1], s[6:7]
	v_cndmask_b32_e64 v51, 0, v12, s[0:1]
	v_or_b32_e32 v12, 24, v24
	v_cmp_le_i32_e64 s[0:1], v12, v3
	v_cmp_gt_i32_e64 s[6:7], v12, v133
	v_exp_f32_e32 v12, v16
	s_and_b64 s[0:1], s[0:1], s[6:7]
	v_cndmask_b32_e64 v52, 0, v12, s[0:1]
	v_or_b32_e32 v12, 25, v24
	v_cmp_le_i32_e64 s[0:1], v12, v3
	v_cmp_gt_i32_e64 s[6:7], v12, v133
	v_exp_f32_e32 v12, v17
	s_and_b64 s[0:1], s[0:1], s[6:7]
	v_cndmask_b32_e64 v53, 0, v12, s[0:1]
	v_or_b32_e32 v12, 26, v24
	v_cmp_le_i32_e64 s[0:1], v12, v3
	v_cmp_gt_i32_e64 s[6:7], v12, v133
	v_exp_f32_e32 v12, v18
	s_and_b64 s[0:1], s[0:1], s[6:7]
	v_cndmask_b32_e64 v54, 0, v12, s[0:1]
	v_or_b32_e32 v12, 27, v24
	v_cmp_le_i32_e64 s[0:1], v12, v3
	v_cmp_gt_i32_e64 s[6:7], v12, v133
	v_exp_f32_e32 v12, v19
	s_and_b64 s[0:1], s[0:1], s[6:7]
	v_cndmask_b32_e64 v55, 0, v12, s[0:1]
	v_add_f32_e32 v12, 0, v4
	v_add_f32_e32 v12, v5, v12
	v_add_f32_e32 v12, v6, v12
	v_add_f32_e32 v12, v7, v12
	v_add_f32_e32 v12, v8, v12
	v_add_f32_e32 v12, v9, v12
	v_add_f32_e32 v12, v10, v12
	v_add_f32_e32 v12, v11, v12
	v_add_f32_e32 v12, v48, v12
	v_add_f32_e32 v12, v49, v12
	v_add_f32_e32 v12, v50, v12
	v_add_f32_e32 v12, v51, v12
	v_add_f32_e32 v12, v52, v12
	v_add_f32_e32 v12, v53, v12
	v_add_f32_e32 v12, v54, v12
	v_cvt_pk_bf16_f32 v4, v4, v5
	v_cvt_pk_bf16_f32 v5, v6, v7
	v_cvt_pk_bf16_f32 v6, v8, v9
	v_cvt_pk_bf16_f32 v7, v10, v11
	v_add_f32_e32 v134, v55, v12
	s_nop 0
	v_mfma_f32_32x32x16_bf16 v[20:35], v[20:23], v[4:7], 0
	v_mfma_f32_32x32x16_bf16 v[4:19], v[44:47], v[4:7], 0
	v_cvt_pk_bf16_f32 v44, v48, v49
	v_cvt_pk_bf16_f32 v45, v50, v51
	v_cvt_pk_bf16_f32 v46, v52, v53
	v_cvt_pk_bf16_f32 v47, v54, v55
	s_nop 1
	v_mfma_f32_32x32x16_bf16 v[20:35], v[40:43], v[44:47], v[20:35]
	v_mfma_f32_32x32x16_bf16 v[4:19], v[36:39], v[44:47], v[4:19]
	s_cbranch_vccnz .LBB0_1200
	v_add_u32_e32 v135, s26, v191
	s_mov_b32 s6, 1
.LBB0_1194:
	s_mov_b32 s0, s6
	s_add_i32 s6, s6, 1
	s_cmp_lt_i32 s6, s27
	s_cselect_b32 s0, s6, s0
	s_lshl_b32 s0, s0, 5
	s_add_i32 s7, s0, s26
	s_ashr_i32 s0, s7, 6
	s_ashr_i32 s1, s0, 31
	s_lshl_b64 s[0:1], s[0:1], 13
	s_add_u32 s8, s56, s0
	s_addc_u32 s59, s57, s1
	s_lshl_b32 s7, s7, 7
	s_and_b32 s7, s7, 0x1000
	s_add_u32 s58, s8, s7
	s_addc_u32 s59, s59, 0
	s_add_u32 s0, s28, s0
	s_addc_u32 s1, s29, s1
	s_waitcnt vmcnt(6)
	v_mov_b64_e32 v[52:53], v[100:101]
	v_mov_b64_e32 v[56:57], v[88:89]
	s_waitcnt vmcnt(5)
	v_mov_b64_e32 v[60:61], v[96:97]
	s_waitcnt vmcnt(4)
	v_mov_b64_e32 v[64:65], v[104:105]
	s_add_u32 s0, s0, s7
	v_mov_b64_e32 v[54:55], v[102:103]
	v_mov_b64_e32 v[58:59], v[90:91]
	v_mov_b64_e32 v[62:63], v[98:99]
	v_mov_b64_e32 v[66:67], v[106:107]
	s_addc_u32 s1, s1, 0
	global_load_dwordx4 v[88:91], v204, s[58:59]
	global_load_dwordx4 v[100:103], v204, s[58:59] offset:1024
	global_load_dwordx4 v[96:99], v204, s[58:59] offset:2048
	global_load_dwordx4 v[104:107], v204, s[58:59] offset:3072
	global_load_dwordx4 v[116:119], v204, s[0:1]
	global_load_dwordx4 v[120:123], v204, s[0:1] offset:1024
	global_load_dwordx4 v[124:127], v204, s[0:1] offset:2048
	global_load_dwordx4 v[128:131], v204, s[0:1] offset:3072
	v_mov_b32 v36, 0
	s_cmp_ge_i32 s6, s27
	v_sub_f32_e32 v36, v36, v183
	v_mov_b32_e32 v37, v36
	v_mov_b64_e32 v[38:39], v[36:37]
	v_mov_b64_e32 v[40:41], v[36:37]
	v_mov_b64_e32 v[42:43], v[36:37]
	v_mov_b64_e32 v[44:45], v[36:37]
	v_mov_b64_e32 v[46:47], v[36:37]
	v_mov_b64_e32 v[48:49], v[36:37]
	v_mov_b64_e32 v[50:51], v[36:37]
	s_mov_b64 s[0:1], -1
	s_nop 0
	v_mfma_f32_32x32x16_bf16 v[36:51], v[56:59], v[80:83], v[36:51]
	v_mfma_f32_32x32x16_bf16 v[36:51], v[52:55], v[76:79], v[36:51]
	v_mfma_f32_32x32x16_bf16 v[36:51], v[60:63], v[72:75], v[36:51]
	v_mfma_f32_32x32x16_bf16 v[36:51], v[64:67], v[68:71], v[36:51]
	s_nop 11
	v_exp_f32_e32 v36, v36
	v_exp_f32_e32 v37, v37
	v_exp_f32_e32 v38, v38
	v_exp_f32_e32 v39, v39
	v_exp_f32_e32 v40, v40
	v_exp_f32_e32 v41, v41
	v_exp_f32_e32 v42, v42
	v_exp_f32_e32 v43, v43
	v_exp_f32_e32 v44, v44
	v_exp_f32_e32 v45, v45
	v_exp_f32_e32 v46, v46
	v_exp_f32_e32 v47, v47
	v_exp_f32_e32 v48, v48
	v_exp_f32_e32 v49, v49
	v_exp_f32_e32 v50, v50
	v_exp_f32_e32 v51, v51
	s_cbranch_scc0 .LBB0_1196
	v_subrev_u32_e32 v53, 27, v135
	v_cmp_le_i32_e32 vcc, v53, v3
	v_cmp_gt_i32_e64 s[0:1], v53, v133
	s_and_b64 vcc, vcc, s[0:1]
	v_cndmask_b32_e32 v52, 0, v36, vcc
	v_cmp_lt_i32_e32 vcc, v53, v3
	v_cmp_ge_i32_e64 s[0:1], v53, v133
	s_and_b64 vcc, vcc, s[0:1]
	v_add_f32_e32 v54, v134, v52
	v_cndmask_b32_e32 v53, 0, v37, vcc
	v_add_f32_e32 v55, v53, v54
	v_subrev_u32_e32 v54, 25, v135
	v_cmp_le_i32_e32 vcc, v54, v3
	v_cmp_gt_i32_e64 s[0:1], v54, v133
	s_and_b64 vcc, vcc, s[0:1]
	v_cndmask_b32_e32 v54, 0, v38, vcc
	v_add_f32_e32 v56, v54, v55
	v_subrev_u32_e32 v55, 24, v135
	v_cmp_le_i32_e32 vcc, v55, v3
	v_cmp_gt_i32_e64 s[0:1], v55, v133
	s_and_b64 vcc, vcc, s[0:1]
	v_cndmask_b32_e32 v55, 0, v39, vcc
	v_add_f32_e32 v57, v55, v56
	v_subrev_u32_e32 v56, 19, v135
	v_cmp_le_i32_e32 vcc, v56, v3
	v_cmp_gt_i32_e64 s[0:1], v56, v133
	s_and_b64 vcc, vcc, s[0:1]
	v_cndmask_b32_e32 v56, 0, v40, vcc
	v_add_f32_e32 v58, v56, v57
	v_subrev_u32_e32 v57, 18, v135
	v_cmp_le_i32_e32 vcc, v57, v3
	v_cmp_gt_i32_e64 s[0:1], v57, v133
	s_and_b64 vcc, vcc, s[0:1]
	v_cndmask_b32_e32 v57, 0, v41, vcc
	v_add_f32_e32 v59, v57, v58
	v_subrev_u32_e32 v58, 17, v135
	v_cmp_le_i32_e32 vcc, v58, v3
	v_cmp_gt_i32_e64 s[0:1], v58, v133
	s_and_b64 vcc, vcc, s[0:1]
	v_cndmask_b32_e32 v58, 0, v42, vcc
	v_add_f32_e32 v60, v58, v59
	v_add_u32_e32 v59, -16, v135
	v_cmp_le_i32_e32 vcc, v59, v3
	v_cmp_gt_i32_e64 s[0:1], v59, v133
	s_and_b64 vcc, vcc, s[0:1]
	v_cndmask_b32_e32 v59, 0, v43, vcc
	v_add_f32_e32 v61, v59, v60
	v_add_u32_e32 v60, -11, v135
	v_cmp_le_i32_e32 vcc, v60, v3
	v_cmp_gt_i32_e64 s[0:1], v60, v133
	s_and_b64 vcc, vcc, s[0:1]
	v_cndmask_b32_e32 v60, 0, v44, vcc
	v_add_f32_e32 v62, v60, v61
	v_add_u32_e32 v61, -10, v135
	v_cmp_le_i32_e32 vcc, v61, v3
	v_cmp_gt_i32_e64 s[0:1], v61, v133
	s_and_b64 vcc, vcc, s[0:1]
	v_cndmask_b32_e32 v61, 0, v45, vcc
	v_add_f32_e32 v63, v61, v62
	v_add_u32_e32 v62, -9, v135
	v_cmp_le_i32_e32 vcc, v62, v3
	v_cmp_gt_i32_e64 s[0:1], v62, v133
	s_and_b64 vcc, vcc, s[0:1]
	v_cndmask_b32_e32 v62, 0, v46, vcc
	v_add_f32_e32 v64, v62, v63
	v_add_u32_e32 v63, -8, v135
	v_cmp_le_i32_e32 vcc, v63, v3
	v_cmp_gt_i32_e64 s[0:1], v63, v133
	s_and_b64 vcc, vcc, s[0:1]
	v_cndmask_b32_e32 v63, 0, v47, vcc
	v_add_f32_e32 v65, v63, v64
	v_add_u32_e32 v64, -3, v135
	v_cmp_le_i32_e32 vcc, v64, v3
	v_cmp_gt_i32_e64 s[0:1], v64, v133
	s_and_b64 vcc, vcc, s[0:1]
	v_cndmask_b32_e32 v64, 0, v48, vcc
	v_add_f32_e32 v66, v64, v65
	v_add_u32_e32 v65, -2, v135
	v_cmp_le_i32_e32 vcc, v65, v3
	v_cmp_gt_i32_e64 s[0:1], v65, v133
	s_and_b64 vcc, vcc, s[0:1]
	v_cndmask_b32_e32 v65, 0, v49, vcc
	v_add_f32_e32 v67, v65, v66
	v_add_u32_e32 v66, -1, v135
	v_cmp_le_i32_e32 vcc, v66, v3
	v_cmp_gt_i32_e64 s[0:1], v66, v133
	s_and_b64 vcc, vcc, s[0:1]
	v_cndmask_b32_e32 v66, 0, v50, vcc
	v_cmp_le_i32_e32 vcc, v135, v3
	v_cmp_gt_i32_e64 s[0:1], v135, v133
	s_and_b64 vcc, vcc, s[0:1]
	v_add_f32_e32 v136, v66, v67
	v_cndmask_b32_e32 v67, 0, v51, vcc
	v_add_f32_e32 v136, v67, v136
	s_mov_b64 s[0:1], 0
